# phase-0 x-row loop: two-row-deep prefetch with alternating register sets, loop-invariant gate constants hoisted (removes per-row vmcnt(0))
# speedup vs baseline: 1.0083x; 1.0076x over previous
.LBB0_129:
	s_or_b64 exec, exec, s[0:1]
	v_ashrrev_i32_e32 v2, 3, v130
	v_readlane_b32 s16, v254, 0
	v_ashrrev_i32_e32 v3, 31, v2
	v_readlane_b32 s18, v254, 2
	v_readlane_b32 s19, v254, 3
	v_readlane_b32 s20, v254, 4
	v_readlane_b32 s21, v254, 5
	v_and_b32_e32 v6, 7, v130
	v_lshl_add_u64 v[4:5], v[2:3], 2, s[18:19]
	s_movk_i32 s0, 0x2c20
	v_mov_b64_e32 v[8:9], s[20:21]
	global_load_dword v1, v[4:5], off
	v_mad_i64_i32 v[4:5], s[4:5], v2, s0, v[8:9]
	v_lshlrev_b32_e32 v134, 2, v6
	v_mov_b32_e32 v135, 0
	v_lshl_add_u64 v[4:5], v[4:5], 0, v[134:135]
	v_add_co_u32_e32 v4, vcc, 0x2000, v4
	s_movk_i32 s1, 0x2000
	s_nop 0
	v_addc_co_u32_e32 v5, vcc, 0, v5, vcc
	global_load_dword v3, v[4:5], off offset:1024
	v_add_u32_e32 v4, 0x100, v130
	v_ashrrev_i32_e32 v4, 3, v4
	v_ashrrev_i32_e32 v5, 31, v4
	v_lshl_add_u64 v[6:7], v[4:5], 2, s[18:19]
	global_load_dword v5, v[6:7], off
	v_mad_i64_i32 v[6:7], s[4:5], v4, s0, v[8:9]
	v_lshl_add_u64 v[6:7], v[6:7], 0, v[134:135]
	v_add_co_u32_e32 v6, vcc, s1, v6
	v_readlane_b32 s17, v254, 1
	s_nop 0
	v_addc_co_u32_e32 v7, vcc, 0, v7, vcc
	global_load_dword v70, v[6:7], off offset:1024
	v_add_u32_e32 v6, 0x200, v130
	v_ashrrev_i32_e32 v6, 3, v6
	v_ashrrev_i32_e32 v7, 31, v6
	v_lshl_add_u64 v[10:11], v[6:7], 2, s[18:19]
	global_load_dword v7, v[10:11], off
	v_mad_i64_i32 v[10:11], s[4:5], v6, s0, v[8:9]
	v_lshl_add_u64 v[10:11], v[10:11], 0, v[134:135]
	v_add_co_u32_e32 v10, vcc, s1, v10
	v_readlane_b32 s22, v254, 6
	s_nop 0
	v_addc_co_u32_e32 v11, vcc, 0, v11, vcc
	global_load_dword v71, v[10:11], off offset:1024
	v_add_u32_e32 v10, 0x300, v130
	v_ashrrev_i32_e32 v10, 3, v10
	v_ashrrev_i32_e32 v11, 31, v10
	v_lshl_add_u64 v[12:13], v[10:11], 2, s[18:19]
	global_load_dword v11, v[12:13], off
	v_mad_i64_i32 v[12:13], s[4:5], v10, s0, v[8:9]
	v_lshl_add_u64 v[12:13], v[12:13], 0, v[134:135]
	v_add_co_u32_e32 v12, vcc, s1, v12
	v_readlane_b32 s23, v254, 7
	s_nop 0
	v_addc_co_u32_e32 v13, vcc, 0, v13, vcc
	global_load_dword v72, v[12:13], off offset:1024
	v_add_u32_e32 v12, 0x400, v130
	v_ashrrev_i32_e32 v12, 3, v12
	v_ashrrev_i32_e32 v13, 31, v12
	v_lshl_add_u64 v[14:15], v[12:13], 2, s[18:19]
	global_load_dword v13, v[14:15], off
	v_mad_i64_i32 v[14:15], s[4:5], v12, s0, v[8:9]
	v_lshl_add_u64 v[14:15], v[14:15], 0, v[134:135]
	v_add_co_u32_e32 v14, vcc, s1, v14
	v_readlane_b32 s24, v254, 8
	s_nop 0
	v_addc_co_u32_e32 v15, vcc, 0, v15, vcc
	global_load_dword v73, v[14:15], off offset:1024
	v_add_u32_e32 v14, 0x500, v130
	v_ashrrev_i32_e32 v14, 3, v14
	v_ashrrev_i32_e32 v15, 31, v14
	v_lshl_add_u64 v[16:17], v[14:15], 2, s[18:19]
	global_load_dword v15, v[16:17], off
	v_mad_i64_i32 v[16:17], s[4:5], v14, s0, v[8:9]
	v_lshl_add_u64 v[16:17], v[16:17], 0, v[134:135]
	v_add_co_u32_e32 v16, vcc, s1, v16
	v_readlane_b32 s25, v254, 9
	s_nop 0
	v_addc_co_u32_e32 v17, vcc, 0, v17, vcc
	global_load_dword v74, v[16:17], off offset:1024
	v_add_u32_e32 v16, 0x600, v130
	v_ashrrev_i32_e32 v16, 3, v16
	v_ashrrev_i32_e32 v17, 31, v16
	v_lshl_add_u64 v[18:19], v[16:17], 2, s[18:19]
	global_load_dword v17, v[18:19], off
	v_mad_i64_i32 v[18:19], s[4:5], v16, s0, v[8:9]
	v_lshl_add_u64 v[18:19], v[18:19], 0, v[134:135]
	v_add_co_u32_e32 v18, vcc, s1, v18
	s_waitcnt vmcnt(11)
	v_mul_f32_e32 v1, v1, v3
	v_addc_co_u32_e32 v19, vcc, 0, v19, vcc
	global_load_dword v75, v[18:19], off offset:1024
	v_add_u32_e32 v18, 0x700, v130
	v_ashrrev_i32_e32 v18, 3, v18
	v_ashrrev_i32_e32 v19, 31, v18
	v_lshl_add_u64 v[20:21], v[18:19], 2, s[18:19]
	global_load_dword v19, v[20:21], off
	v_mad_i64_i32 v[20:21], s[4:5], v18, s0, v[8:9]
	v_lshl_add_u64 v[20:21], v[20:21], 0, v[134:135]
	v_add_co_u32_e32 v20, vcc, s1, v20
	s_waitcnt vmcnt(11)
	v_mul_f32_e32 v3, v5, v70
	v_addc_co_u32_e32 v21, vcc, 0, v21, vcc
	global_load_dword v76, v[20:21], off offset:1024
	v_add_u32_e32 v20, 0x800, v130
	v_ashrrev_i32_e32 v20, 3, v20
	v_ashrrev_i32_e32 v21, 31, v20
	v_lshl_add_u64 v[22:23], v[20:21], 2, s[18:19]
	global_load_dword v21, v[22:23], off
	v_mad_i64_i32 v[22:23], s[4:5], v20, s0, v[8:9]
	v_lshl_add_u64 v[22:23], v[22:23], 0, v[134:135]
	v_add_co_u32_e32 v22, vcc, s1, v22
	s_waitcnt vmcnt(11)
	v_mul_f32_e32 v5, v7, v71
	v_addc_co_u32_e32 v23, vcc, 0, v23, vcc
	global_load_dword v77, v[22:23], off offset:1024
	v_add_u32_e32 v22, 0x900, v130
	v_ashrrev_i32_e32 v22, 3, v22
	v_ashrrev_i32_e32 v23, 31, v22
	v_lshl_add_u64 v[24:25], v[22:23], 2, s[18:19]
	global_load_dword v23, v[24:25], off
	v_mad_i64_i32 v[24:25], s[4:5], v22, s0, v[8:9]
	v_lshl_add_u64 v[24:25], v[24:25], 0, v[134:135]
	v_add_co_u32_e32 v24, vcc, s1, v24
	s_waitcnt vmcnt(11)
	v_mul_f32_e32 v7, v11, v72
	v_addc_co_u32_e32 v25, vcc, 0, v25, vcc
	global_load_dword v78, v[24:25], off offset:1024
	v_add_u32_e32 v24, 0xa00, v130
	v_ashrrev_i32_e32 v24, 3, v24
	v_ashrrev_i32_e32 v25, 31, v24
	v_lshl_add_u64 v[26:27], v[24:25], 2, s[18:19]
	global_load_dword v25, v[26:27], off
	v_mad_i64_i32 v[26:27], s[4:5], v24, s0, v[8:9]
	v_lshl_add_u64 v[26:27], v[26:27], 0, v[134:135]
	v_add_co_u32_e32 v26, vcc, s1, v26
	v_readlane_b32 s26, v254, 10
	s_nop 0
	v_addc_co_u32_e32 v27, vcc, 0, v27, vcc
	global_load_dword v79, v[26:27], off offset:1024
	v_add_u32_e32 v26, 0xb00, v130
	v_ashrrev_i32_e32 v26, 3, v26
	v_ashrrev_i32_e32 v27, 31, v26
	v_lshl_add_u64 v[28:29], v[26:27], 2, s[18:19]
	global_load_dword v27, v[28:29], off
	v_mad_i64_i32 v[28:29], s[4:5], v26, s0, v[8:9]
	v_lshl_add_u64 v[28:29], v[28:29], 0, v[134:135]
	v_add_co_u32_e32 v28, vcc, s1, v28
	s_waitcnt vmcnt(11)
	v_mul_f32_e32 v11, v15, v74
	v_addc_co_u32_e32 v29, vcc, 0, v29, vcc
	global_load_dword v80, v[28:29], off offset:1024
	v_add_u32_e32 v28, 0xc00, v130
	v_ashrrev_i32_e32 v28, 3, v28
	v_ashrrev_i32_e32 v29, 31, v28
	v_lshl_add_u64 v[30:31], v[28:29], 2, s[18:19]
	global_load_dword v29, v[30:31], off
	v_mad_i64_i32 v[30:31], s[4:5], v28, s0, v[8:9]
	v_lshl_add_u64 v[30:31], v[30:31], 0, v[134:135]
	v_add_co_u32_e32 v30, vcc, s1, v30
	v_readlane_b32 s27, v254, 11
	s_nop 0
	v_addc_co_u32_e32 v31, vcc, 0, v31, vcc
	global_load_dword v81, v[30:31], off offset:1024
	v_add_u32_e32 v30, 0xd00, v130
	v_ashrrev_i32_e32 v30, 3, v30
	v_ashrrev_i32_e32 v31, 31, v30
	v_lshl_add_u64 v[32:33], v[30:31], 2, s[18:19]
	global_load_dword v31, v[32:33], off
	v_mad_i64_i32 v[32:33], s[4:5], v30, s0, v[8:9]
	v_lshl_add_u64 v[32:33], v[32:33], 0, v[134:135]
	v_add_co_u32_e32 v32, vcc, s1, v32
	s_waitcnt vmcnt(11)
	v_mul_f32_e32 v15, v19, v76
	v_addc_co_u32_e32 v33, vcc, 0, v33, vcc
	global_load_dword v82, v[32:33], off offset:1024
	v_add_u32_e32 v32, 0xe00, v130
	v_ashrrev_i32_e32 v32, 3, v32
	v_ashrrev_i32_e32 v33, 31, v32
	v_lshl_add_u64 v[34:35], v[32:33], 2, s[18:19]
	global_load_dword v33, v[34:35], off
	v_mad_i64_i32 v[34:35], s[4:5], v32, s0, v[8:9]
	v_lshl_add_u64 v[34:35], v[34:35], 0, v[134:135]
	v_add_co_u32_e32 v34, vcc, s1, v34
	v_readlane_b32 s28, v254, 12
	s_nop 0
	v_addc_co_u32_e32 v35, vcc, 0, v35, vcc
	global_load_dword v83, v[34:35], off offset:1024
	v_add_u32_e32 v34, 0xf00, v130
	v_ashrrev_i32_e32 v34, 3, v34
	v_ashrrev_i32_e32 v35, 31, v34
	v_lshl_add_u64 v[36:37], v[34:35], 2, s[18:19]
	global_load_dword v35, v[36:37], off
	v_mad_i64_i32 v[36:37], s[4:5], v34, s0, v[8:9]
	v_lshl_add_u64 v[36:37], v[36:37], 0, v[134:135]
	v_add_co_u32_e32 v36, vcc, s1, v36
	s_waitcnt vmcnt(11)
	v_mul_f32_e32 v19, v23, v78
	v_addc_co_u32_e32 v37, vcc, 0, v37, vcc
	global_load_dword v84, v[36:37], off offset:1024
	v_add_u32_e32 v36, 0x1000, v130
	v_ashrrev_i32_e32 v36, 3, v36
	v_ashrrev_i32_e32 v37, 31, v36
	v_lshl_add_u64 v[38:39], v[36:37], 2, s[18:19]
	global_load_dword v37, v[38:39], off
	v_mad_i64_i32 v[38:39], s[4:5], v36, s0, v[8:9]
	v_lshl_add_u64 v[38:39], v[38:39], 0, v[134:135]
	v_add_co_u32_e32 v38, vcc, s1, v38
	v_readlane_b32 s29, v254, 13
	s_nop 0
	v_addc_co_u32_e32 v39, vcc, 0, v39, vcc
	global_load_dword v85, v[38:39], off offset:1024
	v_add_u32_e32 v38, 0x1100, v130
	v_ashrrev_i32_e32 v38, 3, v38
	v_ashrrev_i32_e32 v39, 31, v38
	v_lshl_add_u64 v[40:41], v[38:39], 2, s[18:19]
	global_load_dword v39, v[40:41], off
	v_mad_i64_i32 v[40:41], s[4:5], v38, s0, v[8:9]
	v_lshl_add_u64 v[40:41], v[40:41], 0, v[134:135]
	v_add_co_u32_e32 v40, vcc, s1, v40
	s_waitcnt vmcnt(11)
	v_mul_f32_e32 v23, v27, v80
	v_addc_co_u32_e32 v41, vcc, 0, v41, vcc
	global_load_dword v86, v[40:41], off offset:1024
	v_add_u32_e32 v40, 0x1200, v130
	v_ashrrev_i32_e32 v40, 3, v40
	v_ashrrev_i32_e32 v41, 31, v40
	v_lshl_add_u64 v[42:43], v[40:41], 2, s[18:19]
	global_load_dword v41, v[42:43], off
	v_mad_i64_i32 v[42:43], s[4:5], v40, s0, v[8:9]
	v_lshl_add_u64 v[42:43], v[42:43], 0, v[134:135]
	v_add_co_u32_e32 v42, vcc, s1, v42
	v_readlane_b32 s30, v254, 14
	s_nop 0
	v_addc_co_u32_e32 v43, vcc, 0, v43, vcc
	global_load_dword v87, v[42:43], off offset:1024
	v_add_u32_e32 v42, 0x1300, v130
	v_ashrrev_i32_e32 v42, 3, v42
	v_ashrrev_i32_e32 v43, 31, v42
	v_lshl_add_u64 v[44:45], v[42:43], 2, s[18:19]
	global_load_dword v43, v[44:45], off
	v_mad_i64_i32 v[44:45], s[4:5], v42, s0, v[8:9]
	v_lshl_add_u64 v[44:45], v[44:45], 0, v[134:135]
	v_add_co_u32_e32 v44, vcc, s1, v44
	s_waitcnt vmcnt(11)
	v_mul_f32_e32 v27, v31, v82
	v_addc_co_u32_e32 v45, vcc, 0, v45, vcc
	global_load_dword v88, v[44:45], off offset:1024
	v_add_u32_e32 v44, 0x1400, v130
	v_ashrrev_i32_e32 v44, 3, v44
	v_ashrrev_i32_e32 v45, 31, v44
	v_lshl_add_u64 v[46:47], v[44:45], 2, s[18:19]
	global_load_dword v45, v[46:47], off
	v_mad_i64_i32 v[46:47], s[4:5], v44, s0, v[8:9]
	v_lshl_add_u64 v[46:47], v[46:47], 0, v[134:135]
	v_add_co_u32_e32 v46, vcc, s1, v46
	v_readlane_b32 s31, v254, 15
	s_nop 0
	v_addc_co_u32_e32 v47, vcc, 0, v47, vcc
	global_load_dword v89, v[46:47], off offset:1024
	v_add_u32_e32 v46, 0x1500, v130
	v_ashrrev_i32_e32 v46, 3, v46
	v_ashrrev_i32_e32 v47, 31, v46
	v_lshl_add_u64 v[48:49], v[46:47], 2, s[18:19]
	global_load_dword v47, v[48:49], off
	v_mad_i64_i32 v[48:49], s[4:5], v46, s0, v[8:9]
	v_lshl_add_u64 v[48:49], v[48:49], 0, v[134:135]
	v_add_co_u32_e32 v48, vcc, s1, v48
	s_waitcnt vmcnt(11)
	v_mul_f32_e32 v31, v35, v84
	v_addc_co_u32_e32 v49, vcc, 0, v49, vcc
	global_load_dword v90, v[48:49], off offset:1024
	v_add_u32_e32 v48, 0x1600, v130
	v_ashrrev_i32_e32 v48, 3, v48
	v_ashrrev_i32_e32 v49, 31, v48
	v_lshl_add_u64 v[50:51], v[48:49], 2, s[18:19]
	global_load_dword v49, v[50:51], off
	v_mad_i64_i32 v[50:51], s[4:5], v48, s0, v[8:9]
	v_lshl_add_u64 v[50:51], v[50:51], 0, v[134:135]
	v_add_co_u32_e32 v50, vcc, s1, v50
	s_waitcnt vmcnt(9)
	v_mul_f32_e32 v35, v39, v86
	v_addc_co_u32_e32 v51, vcc, 0, v51, vcc
	global_load_dword v91, v[50:51], off offset:1024
	v_add_u32_e32 v50, 0x1700, v130
	v_ashrrev_i32_e32 v50, 3, v50
	v_ashrrev_i32_e32 v51, 31, v50
	v_lshl_add_u64 v[52:53], v[50:51], 2, s[18:19]
	global_load_dword v51, v[52:53], off
	v_mad_i64_i32 v[52:53], s[4:5], v50, s0, v[8:9]
	v_lshl_add_u64 v[52:53], v[52:53], 0, v[134:135]
	v_add_co_u32_e32 v52, vcc, s1, v52
	s_waitcnt vmcnt(7)
	v_mul_f32_e32 v39, v43, v88
	v_addc_co_u32_e32 v53, vcc, 0, v53, vcc
	global_load_dword v92, v[52:53], off offset:1024
	v_add_u32_e32 v52, 0x1800, v130
	v_ashrrev_i32_e32 v52, 3, v52
	v_ashrrev_i32_e32 v53, 31, v52
	v_lshl_add_u64 v[54:55], v[52:53], 2, s[18:19]
	global_load_dword v53, v[54:55], off
	v_mad_i64_i32 v[54:55], s[4:5], v52, s0, v[8:9]
	v_lshl_add_u64 v[54:55], v[54:55], 0, v[134:135]
	v_add_co_u32_e32 v54, vcc, s1, v54
	s_waitcnt vmcnt(5)
	v_mul_f32_e32 v43, v47, v90
	v_addc_co_u32_e32 v55, vcc, 0, v55, vcc
	global_load_dword v93, v[54:55], off offset:1024
	v_add_u32_e32 v54, 0x1900, v130
	v_ashrrev_i32_e32 v54, 3, v54
	v_ashrrev_i32_e32 v55, 31, v54
	v_lshl_add_u64 v[56:57], v[54:55], 2, s[18:19]
	global_load_dword v55, v[56:57], off
	v_mad_i64_i32 v[56:57], s[4:5], v54, s0, v[8:9]
	v_lshl_add_u64 v[56:57], v[56:57], 0, v[134:135]
	v_add_co_u32_e32 v56, vcc, s1, v56
	s_waitcnt vmcnt(3)
	v_mul_f32_e32 v47, v51, v92
	v_addc_co_u32_e32 v57, vcc, 0, v57, vcc
	global_load_dword v94, v[56:57], off offset:1024
	v_add_u32_e32 v56, 0x1a00, v130
	v_ashrrev_i32_e32 v56, 3, v56
	v_ashrrev_i32_e32 v57, 31, v56
	v_lshl_add_u64 v[58:59], v[56:57], 2, s[18:19]
	global_load_dword v57, v[58:59], off
	v_mad_i64_i32 v[58:59], s[4:5], v56, s0, v[8:9]
	v_lshl_add_u64 v[58:59], v[58:59], 0, v[134:135]
	v_add_co_u32_e32 v58, vcc, s1, v58
	s_waitcnt vmcnt(1)
	v_mul_f32_e32 v51, v55, v94
	v_addc_co_u32_e32 v59, vcc, 0, v59, vcc
	global_load_dword v95, v[58:59], off offset:1024
	v_add_u32_e32 v58, 0x1b00, v130
	v_ashrrev_i32_e32 v58, 3, v58
	v_ashrrev_i32_e32 v59, 31, v58
	v_lshl_add_u64 v[60:61], v[58:59], 2, s[18:19]
	global_load_dword v59, v[60:61], off
	v_mad_i64_i32 v[60:61], s[4:5], v58, s0, v[8:9]
	v_lshl_add_u64 v[60:61], v[60:61], 0, v[134:135]
	v_add_co_u32_e32 v60, vcc, s1, v60
	s_nop 1
	v_addc_co_u32_e32 v61, vcc, 0, v61, vcc
	global_load_dword v96, v[60:61], off offset:1024
	v_add_u32_e32 v60, 0x1c00, v130
	v_ashrrev_i32_e32 v60, 3, v60
	v_ashrrev_i32_e32 v61, 31, v60
	v_lshl_add_u64 v[62:63], v[60:61], 2, s[18:19]
	global_load_dword v61, v[62:63], off
	v_mad_i64_i32 v[62:63], s[4:5], v60, s0, v[8:9]
	v_lshl_add_u64 v[62:63], v[62:63], 0, v[134:135]
	v_add_co_u32_e32 v62, vcc, s1, v62
	s_waitcnt vmcnt(1)
	v_mul_f32_e32 v55, v59, v96
	v_addc_co_u32_e32 v63, vcc, 0, v63, vcc
	global_load_dword v97, v[62:63], off offset:1024
	v_add_u32_e32 v62, 0x1d00, v130
	v_ashrrev_i32_e32 v62, 3, v62
	v_ashrrev_i32_e32 v63, 31, v62
	v_lshl_add_u64 v[64:65], v[62:63], 2, s[18:19]
	global_load_dword v63, v[64:65], off
	v_mad_i64_i32 v[64:65], s[4:5], v62, s0, v[8:9]
	v_lshl_add_u64 v[64:65], v[64:65], 0, v[134:135]
	v_add_co_u32_e32 v64, vcc, s1, v64
	s_nop 1
	v_addc_co_u32_e32 v65, vcc, 0, v65, vcc
	global_load_dword v98, v[64:65], off offset:1024
	v_add_u32_e32 v64, 0x1e00, v130
	v_ashrrev_i32_e32 v64, 3, v64
	v_ashrrev_i32_e32 v65, 31, v64
	v_lshl_add_u64 v[66:67], v[64:65], 2, s[18:19]
	global_load_dword v65, v[66:67], off
	v_mad_i64_i32 v[66:67], s[4:5], v64, s0, v[8:9]
	v_lshl_add_u64 v[66:67], v[66:67], 0, v[134:135]
	v_add_co_u32_e32 v66, vcc, s1, v66
	s_waitcnt vmcnt(1)
	v_mul_f32_e32 v59, v63, v98
	v_addc_co_u32_e32 v67, vcc, 0, v67, vcc
	global_load_dword v99, v[66:67], off offset:1024
	v_add_u32_e32 v66, 0x1f00, v130
	v_ashrrev_i32_e32 v66, 3, v66
	v_mad_i64_i32 v[8:9], s[4:5], v66, s0, v[8:9]
	v_lshl_add_u64 v[8:9], v[8:9], 0, v[134:135]
	v_ashrrev_i32_e32 v67, 31, v66
	v_add_co_u32_e32 v8, vcc, s1, v8
	v_lshl_add_u64 v[68:69], v[66:67], 2, s[18:19]
	s_nop 0
	v_addc_co_u32_e32 v9, vcc, 0, v9, vcc
	global_load_dword v67, v[68:69], off
	v_lshlrev_b32_e32 v63, 12, v130
	global_load_dword v8, v[8:9], off offset:1024
	v_and_b32_e32 v63, 0x7000, v63
	v_lshl_add_u32 v2, v2, 2, v63
	ds_write_b32 v2, v1
	v_lshl_add_u32 v1, v4, 2, v63
	ds_write_b32 v1, v3
	v_lshl_add_u32 v1, v6, 2, v63
	ds_write_b32 v1, v5
	v_lshl_add_u32 v1, v10, 2, v63
	v_mul_f32_e32 v9, v13, v73
	ds_write_b32 v1, v7
	v_lshl_add_u32 v1, v12, 2, v63
	ds_write_b32 v1, v9
	v_lshl_add_u32 v1, v14, 2, v63
	v_mul_f32_e32 v13, v17, v75
	ds_write_b32 v1, v11
	v_lshl_add_u32 v1, v16, 2, v63
	ds_write_b32 v1, v13
	v_lshl_add_u32 v1, v18, 2, v63
	v_mul_f32_e32 v17, v21, v77
	ds_write_b32 v1, v15
	v_lshl_add_u32 v1, v20, 2, v63
	ds_write_b32 v1, v17
	v_lshl_add_u32 v1, v22, 2, v63
	v_mul_f32_e32 v21, v25, v79
	ds_write_b32 v1, v19
	v_lshl_add_u32 v1, v24, 2, v63
	ds_write_b32 v1, v21
	v_lshl_add_u32 v1, v26, 2, v63
	v_mul_f32_e32 v25, v29, v81
	ds_write_b32 v1, v23
	v_lshl_add_u32 v1, v28, 2, v63
	ds_write_b32 v1, v25
	v_lshl_add_u32 v1, v30, 2, v63
	v_mul_f32_e32 v29, v33, v83
	ds_write_b32 v1, v27
	v_lshl_add_u32 v1, v32, 2, v63
	ds_write_b32 v1, v29
	v_lshl_add_u32 v1, v34, 2, v63
	v_mul_f32_e32 v33, v37, v85
	ds_write_b32 v1, v31
	v_lshl_add_u32 v1, v36, 2, v63
	ds_write_b32 v1, v33
	v_lshl_add_u32 v1, v38, 2, v63
	v_mul_f32_e32 v37, v41, v87
	ds_write_b32 v1, v35
	v_lshl_add_u32 v1, v40, 2, v63
	ds_write_b32 v1, v37
	v_lshl_add_u32 v1, v42, 2, v63
	v_mul_f32_e32 v41, v45, v89
	ds_write_b32 v1, v39
	v_lshl_add_u32 v1, v44, 2, v63
	ds_write_b32 v1, v41
	v_lshl_add_u32 v1, v46, 2, v63
	v_mul_f32_e32 v45, v49, v91
	ds_write_b32 v1, v43
	v_lshl_add_u32 v1, v48, 2, v63
	ds_write_b32 v1, v45
	v_lshl_add_u32 v1, v50, 2, v63
	v_mul_f32_e32 v49, v53, v93
	ds_write_b32 v1, v47
	v_lshl_add_u32 v1, v52, 2, v63
	ds_write_b32 v1, v49
	v_lshl_add_u32 v1, v54, 2, v63
	v_mul_f32_e32 v53, v57, v95
	ds_write_b32 v1, v51
	v_lshl_add_u32 v1, v56, 2, v63
	ds_write_b32 v1, v53
	v_lshl_add_u32 v1, v58, 2, v63
	v_mul_f32_e32 v57, v61, v97
	ds_write_b32 v1, v55
	v_lshl_add_u32 v1, v60, 2, v63
	ds_write_b32 v1, v57
	v_lshl_add_u32 v1, v62, 2, v63
	s_waitcnt vmcnt(2)
	v_mul_f32_e32 v61, v65, v99
	ds_write_b32 v1, v59
	v_lshl_add_u32 v1, v64, 2, v63
	s_mov_b32 s0, 0x10000
	ds_write_b32 v1, v61
	v_lshl_add_u32 v1, v66, 2, v63
	s_waitcnt vmcnt(0)
	v_mul_f32_e32 v8, v67, v8
	v_cmp_gt_i32_e32 vcc, s0, v162
	ds_write_b32 v1, v8
	s_waitcnt lgkmcnt(0)
	s_barrier
	s_and_saveexec_b64 s[16:17], vcc
	s_cbranch_execz .LBB0_142
	v_ashrrev_i32_e32 v163, 31, v162
	v_readlane_b32 s36, v254, 0
	v_lshlrev_b64 v[2:3], 12, v[162:163]
	v_readlane_b32 s37, v254, 1
	v_lshlrev_b32_e32 v134, 4, v132
	v_mbcnt_lo_u32_b32 v1, -1, 0
	v_lshl_add_u64 v[2:3], s[36:37], 0, v[2:3]
	v_lshl_add_u64 v[2:3], v[2:3], 0, v[134:135]
	global_load_dwordx4 v[158:161], v[2:3], off
	global_load_dwordx4 v[146:149], v[2:3], off offset:1024
	global_load_dwordx4 v[150:153], v[2:3], off offset:2048
	global_load_dwordx4 v[154:157], v[2:3], off offset:3072
	v_mbcnt_hi_u32_b32 v2, -1, v1
	v_and_b32_e32 v1, 64, v2
	v_add_u32_e32 v3, 64, v1
	v_xor_b32_e32 v1, 32, v2
	v_cmp_lt_i32_e32 vcc, v1, v3
	v_xor_b32_e32 v4, 16, v2
	v_readlane_b32 s40, v254, 4
	v_cndmask_b32_e32 v1, v2, v1, vcc
	v_cmp_lt_i32_e32 vcc, v4, v3
	v_readlane_b32 s41, v254, 5
	v_readlane_b32 s42, v254, 6
	v_cndmask_b32_e32 v4, v2, v4, vcc
	v_lshlrev_b32_e32 v178, 2, v4
	v_xor_b32_e32 v4, 8, v2
	v_cmp_lt_i32_e32 vcc, v4, v3
	v_readlane_b32 s43, v254, 7
	v_readlane_b32 s44, v254, 8
	v_cndmask_b32_e32 v4, v2, v4, vcc
	v_lshlrev_b32_e32 v179, 2, v4
	v_xor_b32_e32 v4, 4, v2
	v_cmp_lt_i32_e32 vcc, v4, v3
	v_readlane_b32 s45, v254, 9
	v_readlane_b32 s46, v254, 10
	v_cndmask_b32_e32 v4, v2, v4, vcc
	v_lshlrev_b32_e32 v180, 2, v4
	v_xor_b32_e32 v4, 2, v2
	v_cmp_lt_i32_e32 vcc, v4, v3
	v_readlane_b32 s47, v254, 11
	v_readlane_b32 s48, v254, 12
	v_cndmask_b32_e32 v4, v2, v4, vcc
	v_lshlrev_b32_e32 v181, 2, v4
	v_xor_b32_e32 v4, 1, v2
	v_cmp_lt_i32_e32 vcc, v4, v3
	v_readlane_b32 s49, v254, 13
	v_readlane_b32 s50, v254, 14
	v_cndmask_b32_e32 v2, v2, v4, vcc
	v_lshlrev_b32_e32 v182, 2, v2
	v_and_b32_e32 v2, 1, v130
	v_cmp_eq_u32_e64 s[0:1], 0, v2
	v_and_b32_e32 v2, 2, v130
	v_cmp_eq_u32_e64 s[4:5], 0, v2
	v_and_b32_e32 v2, 4, v130
	v_cmp_eq_u32_e64 s[6:7], 0, v2
	ds_read_b128 v[2:5], v134
	ds_read_b128 v[6:9], v134 offset:1024
	ds_read_b128 v[10:13], v134 offset:4096
	ds_read_b128 v[14:17], v134 offset:5120
	ds_read_b128 v[18:21], v134 offset:8192
	ds_read_b128 v[22:25], v134 offset:9216
	ds_read_b128 v[26:29], v134 offset:12288
	ds_read_b128 v[30:33], v134 offset:13312
	ds_read_b128 v[34:37], v134 offset:16384
	ds_read_b128 v[38:41], v134 offset:17408
	ds_read_b128 v[42:45], v134 offset:20480
	ds_read_b128 v[46:49], v134 offset:21504
	ds_read_b128 v[50:53], v134 offset:24576
	ds_read_b128 v[54:57], v134 offset:25600
	ds_read_b128 v[58:61], v134 offset:28672
	ds_read_b128 v[62:65], v134 offset:29696
	ds_read_b128 v[66:69], v134 offset:2048
	ds_read_b128 v[70:73], v134 offset:3072
	ds_read_b128 v[74:77], v134 offset:6144
	ds_read_b128 v[78:81], v134 offset:7168
	ds_read_b128 v[82:85], v134 offset:10240
	ds_read_b128 v[86:89], v134 offset:11264
	ds_read_b128 v[90:93], v134 offset:14336
	ds_read_b128 v[94:97], v134 offset:15360
	ds_read_b128 v[98:101], v134 offset:18432
	ds_read_b128 v[102:105], v134 offset:19456
	ds_read_b128 v[106:109], v134 offset:22528
	ds_read_b128 v[110:113], v134 offset:23552
	ds_read_b128 v[114:117], v134 offset:26624
	ds_read_b128 v[118:121], v134 offset:27648
	ds_read_b128 v[122:125], v134 offset:30720
	ds_read_b128 v[126:129], v134 offset:31744
	v_readlane_b32 s51, v254, 15
	v_lshlrev_b32_e32 v130, 2, v130
	v_readlane_b32 s40, v254, 16
	v_readlane_b32 s38, v254, 2
	v_readlane_b32 s39, v254, 3
	v_and_b32_e32 v130, 12, v130
	v_mov_b32_e32 v131, v135
	v_readlane_b32 s41, v254, 17
	v_readlane_b32 s42, v254, 18
	v_readlane_b32 s43, v254, 19
	v_readlane_b32 s44, v254, 20
	v_lshl_add_u64 v[168:169], s[36:37], 0, v[134:135]
	v_mov_b64_e32 v[134:135], 0x36b00000
	s_ashr_i32 s3, s2, 31
	v_lshlrev_b64 v[172:173], 4, v[162:163]
	v_lshlrev_b64 v[174:175], 11, v[162:163]
	v_lshlrev_b32_e32 v1, 2, v1
	v_cmp_eq_u32_e64 s[8:9], 0, v132
	v_cmp_gt_u32_e64 s[10:11], 8, v132
	v_cmp_lt_u32_e64 s[12:13], 3, v132
	v_lshl_add_u64 v[164:165], s[42:43], 0, v[130:131]
	v_lshl_add_u64 v[166:167], s[40:41], 0, v[130:131]
	v_lshl_add_u64 v[170:171], v[162:163], 2, v[134:135]
	s_lshl_b64 s[18:19], s[2:3], 2
	v_or_b32_e32 v172, v172, v130
	s_lshl_b64 s[20:21], s[2:3], 4
	v_lshl_or_b32 v174, v132, 3, v174
	s_lshl_b64 s[22:23], s[2:3], 11
	s_mov_b64 s[24:25], 0
	s_mov_b32 s3, 0xffff
	v_mov_b32_e32 v163, 0x358637bd
	s_mov_b32 s33, 0x800000
	s_mov_b32 s34, 0xbfb8aa3b
	s_mov_b32 s35, 0x42ce8ed0
	s_mov_b32 s36, 0xc2b17218
	s_mov_b32 s37, 0x7f800000
	s_mov_b32 s38, 0x41a00000
	s_mov_b32 s39, 0x3fb8aa3b
	s_mov_b32 s40, 0xc2ce8ed0
	s_mov_b32 s41, 0x42b17218
	s_mov_b32 s42, 0x3f2aaaab
	v_mov_b32_e32 v183, 0x3ecc95a3
	s_mov_b32 s43, 0x3f317218
	s_mov_b32 s44, 0x33800000
	v_mov_b32_e32 v184, 0x7f800000
	v_mov_b32_e32 v176, 0x3f317218
	v_readlane_b32 s45, v254, 21
	v_readlane_b32 s46, v254, 22
	v_readlane_b32 s47, v254, 23
	v_readlane_b32 s48, v254, 24
	v_readlane_b32 s49, v254, 25
	v_readlane_b32 s50, v254, 26
	v_readlane_b32 s51, v254, 27
	v_readlane_b32 s52, v254, 28
	v_readlane_b32 s53, v254, 29
	v_readlane_b32 s54, v254, 30
	v_readlane_b32 s55, v254, 31
	global_load_dword v252, v[164:165], off
	global_load_dword v253, v[166:167], off
	v_add_u32_e32 v228, s2, v162
	v_min_i32_e32 v228, 0xffff, v228
	v_ashrrev_i32_e32 v229, 31, v228
	v_lshlrev_b64 v[228:229], 12, v[228:229]
	v_lshl_add_u64 v[228:229], v[168:169], 0, v[228:229]
	global_load_dwordx4 v[142:145], v[228:229], off
	global_load_dwordx4 v[138:141], v[228:229], off offset:1024
	global_load_dwordx4 v[134:137], v[228:229], off offset:2048
	global_load_dwordx4 v[130:133], v[228:229], off offset:3072
	s_waitcnt vmcnt(0)
	s_mov_b32 s32, 0
	s_branch .LBB0_134
.LBB0_131:
	s_or_b64 exec, exec, s[30:31]
	v_mov_b32_e32 v147, v253
	v_mul_f32_e32 v148, 0x3fb8aa3b, v147
	v_rndne_f32_e32 v149, v148
	v_fma_f32 v150, v147, s39, -v148
	v_sub_f32_e32 v148, v148, v149
	v_fmac_f32_e32 v150, 0x32a5705f, v147
	v_add_f32_e32 v148, v148, v150
	v_cvt_i32_f32_e32 v149, v149
	v_exp_f32_e32 v148, v148
	v_cmp_ngt_f32_e32 vcc, s40, v147
	v_ldexp_f32 v148, v148, v149
	s_nop 0
	v_cndmask_b32_e32 v148, 0, v148, vcc
	v_cmp_nlt_f32_e32 vcc, s41, v147
	s_nop 1
	v_cndmask_b32_e32 v147, v184, v148, vcc
	v_mul_f32_e64 v149, v146, -v147
	v_mov_b64_e32 v[146:147], 0x36d00000

.LBB0_133:
	s_or_b64 exec, exec, s[26:27]
	v_cmp_lt_i32_e32 vcc, s3, v162
	v_lshl_add_u64 v[170:171], v[170:171], 0, s[18:19]
	v_lshl_add_u64 v[172:173], v[172:173], 0, s[20:21]
	v_lshl_add_u64 v[174:175], v[174:175], 0, s[22:23]
	s_or_b64 s[24:25], vcc, s[24:25]
	s_waitcnt vmcnt(12)
	s_cmp_eq_u32 s32, 0
	s_cbranch_scc0 .Lp0r_cpy
	v_mov_b32_e32 v158, v142
	v_mov_b32_e32 v159, v143
	v_mov_b32_e32 v160, v144
	v_mov_b32_e32 v161, v145
	v_mov_b32_e32 v146, v138
	v_mov_b32_e32 v147, v139
	v_mov_b32_e32 v148, v140
	v_mov_b32_e32 v149, v141
	v_mov_b32_e32 v150, v134
	v_mov_b32_e32 v151, v135
	v_mov_b32_e32 v152, v136
	v_mov_b32_e32 v153, v137
	v_mov_b32_e32 v154, v130
	v_mov_b32_e32 v155, v131
	v_mov_b32_e32 v156, v132
	v_mov_b32_e32 v157, v133
	s_branch .Lp0r_cpd
.Lp0r_cpy:
	v_mov_b32_e32 v158, v224
	v_mov_b32_e32 v159, v225
	v_mov_b32_e32 v160, v226
	v_mov_b32_e32 v161, v227
	v_mov_b32_e32 v146, v220
	v_mov_b32_e32 v147, v221
	v_mov_b32_e32 v148, v222
	v_mov_b32_e32 v149, v223
	v_mov_b32_e32 v150, v216
	v_mov_b32_e32 v151, v217
	v_mov_b32_e32 v152, v218
	v_mov_b32_e32 v153, v219
	v_mov_b32_e32 v154, v212
	v_mov_b32_e32 v155, v213
	v_mov_b32_e32 v156, v214
	v_mov_b32_e32 v157, v215
.Lp0r_cpd:
	s_xor_b32 s32, s32, 1
	s_andn2_b64 exec, exec, s[24:25]
	s_cbranch_execz .LBB0_142
.LBB0_134:
	v_pk_mul_f32 v[198:199], v[158:159], v[158:159]
	v_pk_mul_f32 v[200:201], v[146:147], v[146:147]
	v_pk_mul_f32 v[194:195], v[160:161], v[160:161]
	v_pk_mul_f32 v[196:197], v[148:149], v[148:149]
	v_mov_b32_e32 v202, v198
	v_mov_b32_e32 v203, v200
	v_mov_b32_e32 v200, v199
	v_pk_add_f32 v[198:199], v[202:203], v[200:201]
	v_mov_b32_e32 v200, v194
	v_mov_b32_e32 v201, v196
	s_waitcnt lgkmcnt(14)
	v_mul_f32_e32 v177, v159, v3
	v_pk_add_f32 v[198:199], v[200:201], v[198:199]
	v_mov_b32_e32 v196, v195
	v_fmac_f32_e32 v177, v158, v2
	v_pk_add_f32 v[194:195], v[196:197], v[198:199]
	v_mul_f32_e32 v196, v147, v7
	v_fmac_f32_e32 v177, v160, v4
	v_fmac_f32_e32 v196, v146, v6
	v_mul_f32_e32 v202, v151, v67
	v_fmac_f32_e32 v177, v161, v5
	v_fmac_f32_e32 v196, v148, v8
	v_fmac_f32_e32 v202, v150, v66
	v_add_f32_e32 v177, 0, v177
	s_waitcnt lgkmcnt(0)
	v_mul_f32_e32 v185, v159, v11
	v_fmac_f32_e32 v196, v149, v9
	v_fmac_f32_e32 v202, v152, v68
	v_fmac_f32_e32 v185, v158, v10
	v_add_f32_e32 v177, v177, v196
	v_mul_f32_e32 v196, v147, v15
	v_fmac_f32_e32 v202, v153, v69
	v_fmac_f32_e32 v185, v160, v12
	v_fmac_f32_e32 v196, v146, v14
	v_add_f32_e32 v177, v177, v202
	s_waitcnt lgkmcnt(13)
	v_mul_f32_e32 v202, v151, v75
	v_fmac_f32_e32 v185, v161, v13
	v_fmac_f32_e32 v196, v148, v16
	v_fmac_f32_e32 v202, v150, v74
	v_add_f32_e32 v185, 0, v185
	v_mul_f32_e32 v186, v159, v19
	v_fmac_f32_e32 v196, v149, v17
	v_fmac_f32_e32 v202, v152, v76
	v_fmac_f32_e32 v186, v158, v18
	v_add_f32_e32 v185, v185, v196
	v_mul_f32_e32 v196, v147, v23
	v_fmac_f32_e32 v202, v153, v77
	v_fmac_f32_e32 v186, v160, v20
	v_fmac_f32_e32 v196, v146, v22
	v_add_f32_e32 v185, v185, v202
	s_waitcnt lgkmcnt(11)
	v_mul_f32_e32 v202, v151, v83
	v_fmac_f32_e32 v186, v161, v21
	v_fmac_f32_e32 v196, v148, v24
	v_fmac_f32_e32 v202, v150, v82
	v_add_f32_e32 v204, 0, v186
	v_mul_f32_e32 v186, v159, v27
	v_fmac_f32_e32 v196, v149, v25
	v_fmac_f32_e32 v202, v152, v84
	v_fmac_f32_e32 v186, v158, v26
	v_add_f32_e32 v196, v204, v196
	v_mul_f32_e32 v197, v147, v31
	v_fmac_f32_e32 v202, v153, v85
	v_fmac_f32_e32 v186, v160, v28
	v_fmac_f32_e32 v197, v146, v30
	v_add_f32_e32 v202, v196, v202
	s_waitcnt lgkmcnt(9)
	v_mul_f32_e32 v196, v151, v91
	v_fmac_f32_e32 v186, v161, v29
	v_fmac_f32_e32 v197, v148, v32
	v_fmac_f32_e32 v196, v150, v90
	v_add_u32_e32 v162, s2, v162
	v_add_f32_e32 v205, 0, v186
	v_mul_f32_e32 v186, v159, v35
	v_fmac_f32_e32 v197, v149, v33
	v_fmac_f32_e32 v196, v152, v92
	v_add_u32_e32 v228, s2, v162
	v_min_i32_e32 v228, 0xffff, v228
	v_fmac_f32_e32 v186, v158, v34
	v_add_f32_e32 v197, v205, v197
	v_mul_f32_e32 v198, v147, v39
	v_fmac_f32_e32 v196, v153, v93
	v_ashrrev_i32_e32 v229, 31, v228
	v_fmac_f32_e32 v186, v160, v36
	v_fmac_f32_e32 v198, v146, v38
	v_add_f32_e32 v203, v197, v196
	s_waitcnt lgkmcnt(7)
	v_mul_f32_e32 v196, v151, v99
	v_lshlrev_b64 v[228:229], 12, v[228:229]
	v_fmac_f32_e32 v186, v161, v37
	v_fmac_f32_e32 v198, v148, v40
	v_fmac_f32_e32 v196, v150, v98
	v_lshl_add_u64 v[228:229], v[168:169], 0, v[228:229]
	v_add_f32_e32 v206, 0, v186
	v_mul_f32_e32 v186, v159, v43
	v_fmac_f32_e32 v198, v149, v41
	v_fmac_f32_e32 v196, v152, v100
	s_cmp_eq_u32 s32, 0
	s_cbranch_scc0 .Lp0r_ldx
	global_load_dwordx4 v[224:227], v[228:229], off
	global_load_dwordx4 v[220:223], v[228:229], off offset:1024
	global_load_dwordx4 v[216:219], v[228:229], off offset:2048
	global_load_dwordx4 v[212:215], v[228:229], off offset:3072
	s_branch .Lp0r_ldd
.Lp0r_ldx:
	global_load_dwordx4 v[142:145], v[228:229], off
	global_load_dwordx4 v[138:141], v[228:229], off offset:1024
	global_load_dwordx4 v[134:137], v[228:229], off offset:2048
	global_load_dwordx4 v[130:133], v[228:229], off offset:3072
.Lp0r_ldd:
	v_fmac_f32_e32 v186, v158, v42
	v_add_f32_e32 v198, v206, v198
	v_mul_f32_e32 v199, v147, v47
	v_fmac_f32_e32 v196, v153, v101
	v_fmac_f32_e32 v186, v160, v44
	v_fmac_f32_e32 v199, v146, v46
	v_add_f32_e32 v198, v198, v196
	s_waitcnt lgkmcnt(5)
	v_mul_f32_e32 v196, v151, v107
	v_fmac_f32_e32 v186, v161, v45
	v_fmac_f32_e32 v199, v148, v48
	v_fmac_f32_e32 v196, v150, v106
	v_add_f32_e32 v207, 0, v186
	v_mul_f32_e32 v186, v159, v51
	v_fmac_f32_e32 v199, v149, v49
	v_fmac_f32_e32 v196, v152, v108
	v_fmac_f32_e32 v186, v158, v50
	v_add_f32_e32 v199, v207, v199
	v_mul_f32_e32 v200, v147, v55
	v_fmac_f32_e32 v196, v153, v109
	v_fmac_f32_e32 v186, v160, v52
	v_fmac_f32_e32 v200, v146, v54
	v_add_f32_e32 v199, v199, v196
	s_waitcnt lgkmcnt(3)
	v_mul_f32_e32 v196, v151, v115
	v_fmac_f32_e32 v186, v161, v53
	v_fmac_f32_e32 v200, v148, v56
	v_fmac_f32_e32 v196, v150, v114
	v_add_f32_e32 v209, 0, v186
	v_mul_f32_e32 v186, v159, v59
	v_fmac_f32_e32 v200, v149, v57
	v_fmac_f32_e32 v196, v152, v116
	v_fmac_f32_e32 v186, v158, v58
	v_add_f32_e32 v200, v209, v200
	v_mul_f32_e32 v201, v147, v63
	v_fmac_f32_e32 v196, v153, v117
	v_fmac_f32_e32 v186, v160, v60
	v_fmac_f32_e32 v201, v146, v62
	v_add_f32_e32 v200, v200, v196
	s_waitcnt lgkmcnt(1)
	v_mul_f32_e32 v196, v151, v123
	v_fmac_f32_e32 v186, v161, v61
	v_fmac_f32_e32 v201, v148, v64
	v_fmac_f32_e32 v196, v150, v122
	v_add_f32_e32 v210, 0, v186
	v_fmac_f32_e32 v201, v149, v65
	v_fmac_f32_e32 v196, v152, v124
	v_pk_mul_f32 v[190:191], v[154:155], v[154:155]
	v_pk_mul_f32 v[192:193], v[150:151], v[150:151]
	v_add_f32_e32 v201, v210, v201
	v_fmac_f32_e32 v196, v153, v125
	v_pk_mul_f32 v[186:187], v[156:157], v[156:157]
	v_pk_mul_f32 v[188:189], v[152:153], v[152:153]
	v_add_f32_e32 v201, v201, v196
	v_mov_b32_e32 v196, v190
	v_mov_b32_e32 v197, v192
	v_mov_b32_e32 v192, v191
	v_pk_add_f32 v[190:191], v[196:197], v[192:193]
	v_mov_b32_e32 v192, v186
	v_mov_b32_e32 v193, v188
	v_pk_add_f32 v[190:191], v[192:193], v[190:191]
	v_mov_b32_e32 v188, v187
	v_pk_add_f32 v[186:187], v[188:189], v[190:191]
	v_add_f32_e32 v192, v194, v195
	v_add_f32_e32 v187, v187, v192
	v_add_f32_e32 v186, v186, v187
	ds_bpermute_b32 v187, v1, v186
	v_mul_f32_e32 v188, v155, v71
	v_fmac_f32_e32 v188, v154, v70
	v_fmac_f32_e32 v188, v156, v72
	v_fmac_f32_e32 v188, v157, v73
	s_waitcnt lgkmcnt(0)
	v_add_f32_e32 v186, v186, v187
	ds_bpermute_b32 v187, v178, v186
	v_add_f32_e32 v177, v177, v188
	v_mul_f32_e32 v188, v155, v79
	v_fmac_f32_e32 v188, v154, v78
	v_fmac_f32_e32 v188, v156, v80
	s_waitcnt lgkmcnt(0)
	v_add_f32_e32 v186, v186, v187
	ds_bpermute_b32 v187, v179, v186
	v_fmac_f32_e32 v188, v157, v81
	v_add_f32_e32 v185, v185, v188
	v_mul_f32_e32 v188, v155, v87
	v_mul_f32_e32 v189, v155, v95
	s_waitcnt lgkmcnt(0)
	v_add_f32_e32 v186, v186, v187
	ds_bpermute_b32 v187, v180, v186
	v_fmac_f32_e32 v188, v154, v86
	v_fmac_f32_e32 v189, v154, v94
	v_mul_f32_e32 v190, v155, v103
	v_mul_f32_e32 v191, v155, v111
	v_fmac_f32_e32 v188, v156, v88
	v_fmac_f32_e32 v189, v156, v96
	v_fmac_f32_e32 v190, v154, v102
	v_fmac_f32_e32 v191, v154, v110
	v_mul_f32_e32 v192, v155, v119
	v_mul_f32_e32 v193, v155, v127
	v_fmac_f32_e32 v188, v157, v89
	v_fmac_f32_e32 v189, v157, v97
	v_fmac_f32_e32 v190, v156, v104
	v_fmac_f32_e32 v191, v156, v112
	v_fmac_f32_e32 v192, v154, v118
	v_fmac_f32_e32 v193, v154, v126
	v_add_f32_e32 v188, v202, v188
	v_add_f32_e32 v189, v203, v189
	v_fmac_f32_e32 v190, v157, v105
	v_fmac_f32_e32 v191, v157, v113
	v_fmac_f32_e32 v192, v156, v120
	v_fmac_f32_e32 v193, v156, v128
	v_add_f32_e32 v190, v198, v190
	v_add_f32_e32 v191, v199, v191
	v_fmac_f32_e32 v192, v157, v121
	v_fmac_f32_e32 v193, v157, v129
	s_waitcnt lgkmcnt(0)
	v_add_f32_e32 v186, v186, v187
	v_cndmask_b32_e64 v187, v188, v189, s[0:1]
	v_add_f32_e32 v192, v200, v192
	v_cndmask_b32_e64 v194, v177, v185, s[0:1]
	v_add_f32_e32 v193, v201, v193
	v_cndmask_b32_e64 v177, v185, v177, s[0:1]
	v_cndmask_b32_e64 v185, v189, v188, s[0:1]
	ds_bpermute_b32 v187, v182, v187
	v_cndmask_b32_e64 v188, v190, v191, s[0:1]
	ds_bpermute_b32 v188, v182, v188
	v_cndmask_b32_e64 v189, v192, v193, s[0:1]
	ds_bpermute_b32 v194, v182, v194
	ds_bpermute_b32 v189, v182, v189
	s_waitcnt lgkmcnt(3)
	v_add_f32_e32 v185, v185, v187
	v_cndmask_b32_e64 v187, v191, v190, s[0:1]
	s_waitcnt lgkmcnt(2)
	v_add_f32_e32 v187, v187, v188
	v_cndmask_b32_e64 v188, v193, v192, s[0:1]
	s_waitcnt lgkmcnt(1)
	v_add_f32_e32 v177, v177, v194
	s_waitcnt lgkmcnt(0)
	v_add_f32_e32 v188, v188, v189
	v_cndmask_b32_e64 v189, v177, v185, s[4:5]
	v_cndmask_b32_e64 v190, v187, v188, s[4:5]
	ds_bpermute_b32 v189, v181, v189
	ds_bpermute_b32 v190, v181, v190
	v_cndmask_b32_e64 v177, v185, v177, s[4:5]
	v_cndmask_b32_e64 v185, v188, v187, s[4:5]
	ds_bpermute_b32 v191, v181, v186
	s_waitcnt lgkmcnt(2)
	v_add_f32_e32 v177, v177, v189
	s_waitcnt lgkmcnt(1)
	v_add_f32_e32 v185, v185, v190
	v_cndmask_b32_e64 v187, v177, v185, s[6:7]
	ds_bpermute_b32 v187, v180, v187
	v_cndmask_b32_e64 v177, v185, v177, s[6:7]
	s_waitcnt lgkmcnt(1)
	v_add_f32_e32 v186, v186, v191
	ds_bpermute_b32 v188, v182, v186
	v_cvt_pk_bf16_f32 v158, v158, v159
	s_waitcnt lgkmcnt(1)
	v_add_f32_e32 v177, v177, v187
	ds_bpermute_b32 v185, v179, v177
	v_cvt_pk_bf16_f32 v159, v160, v161
	s_waitcnt lgkmcnt(1)
	v_add_f32_e32 v186, v186, v188
	v_fmamk_f32 v186, v186, 0x3a800000, v163
	v_mul_f32_e32 v187, 0x4b800000, v186
	s_waitcnt lgkmcnt(0)
	v_add_f32_e32 v177, v177, v185
	ds_bpermute_b32 v185, v178, v177
	v_cmp_gt_f32_e32 vcc, s33, v186
	v_lshl_add_u64 v[160:161], s[92:93], 0, v[174:175]
	v_cvt_pk_bf16_f32 v146, v146, v147
	v_cndmask_b32_e32 v186, v186, v187, vcc
	v_rsq_f32_e32 v186, v186
	s_waitcnt lgkmcnt(0)
	v_add_f32_e32 v177, v177, v185
	ds_bpermute_b32 v185, v1, v177
	v_cvt_pk_bf16_f32 v147, v148, v149
	global_store_dwordx2 v[160:161], v[146:147], off offset:512
	v_cvt_pk_bf16_f32 v146, v150, v151
	v_cvt_pk_bf16_f32 v147, v152, v153
	v_mul_f32_e32 v187, 0x45800000, v186
	global_store_dwordx2 v[160:161], v[146:147], off offset:1024
	v_cvt_pk_bf16_f32 v146, v154, v155
	v_cvt_pk_bf16_f32 v147, v156, v157
	global_store_dwordx2 v[160:161], v[146:147], off offset:1536
	v_cndmask_b32_e32 v146, v186, v187, vcc
	global_store_dwordx2 v[160:161], v[158:159], off
	s_and_saveexec_b64 s[26:27], s[8:9]
	s_cbranch_execz .LBB0_136
	v_lshl_add_u64 v[148:149], s[92:93], 0, v[170:171]
	global_store_dword v[148:149], v146, off

.LBB0_139:
	s_or_saveexec_b64 s[28:29], s[28:29]
	v_mov_b64_e32 v[146:147], 0x36e00000
	s_xor_b64 exec, exec, s[28:29]
	s_cbranch_execz .LBB0_132
	v_mov_b32_e32 v146, v252
	v_add_f32_e32 v146, v148, v146
	v_cmp_nlt_f32_e32 vcc, s38, v146
	s_and_saveexec_b64 s[30:31], vcc
	s_cbranch_execz .LBB0_131
	v_mul_f32_e32 v147, 0x3fb8aa3b, v146
	v_rndne_f32_e32 v148, v147
	v_sub_f32_e32 v149, v147, v148
	v_fma_f32 v147, v146, s39, -v147
	v_fmac_f32_e32 v147, 0x32a5705f, v146
	v_add_f32_e32 v147, v149, v147
	v_cvt_i32_f32_e32 v148, v148
	v_exp_f32_e32 v147, v147
	v_cmp_ngt_f32_e32 vcc, s40, v146
	v_ldexp_f32 v147, v147, v148
	s_nop 0
	v_cndmask_b32_e32 v147, 0, v147, vcc
	v_cmp_nlt_f32_e32 vcc, s41, v146
	s_nop 1
	v_cndmask_b32_e32 v160, v184, v147, vcc
	v_add_f32_e32 v148, 1.0, v160
	v_add_f32_e32 v146, -1.0, v148
	v_sub_f32_e32 v147, v146, v148
	v_add_f32_e32 v147, 1.0, v147
	v_sub_f32_e32 v146, v160, v146
	v_add_f32_e32 v149, v146, v147
	v_frexp_mant_f32_e32 v150, v148
	v_cvt_f64_f32_e32 v[146:147], v148
	v_frexp_exp_i32_f64_e32 v146, v[146:147]
	v_cmp_gt_f32_e32 vcc, s42, v150
	s_nop 1
	v_subbrev_co_u32_e32 v154, vcc, 0, v146, vcc
	v_sub_u32_e32 v146, 0, v154
	v_ldexp_f32 v147, v148, v146
	v_add_f32_e32 v148, -1.0, v147
	v_add_f32_e32 v150, 1.0, v147
	v_ldexp_f32 v146, v149, v146
	v_add_f32_e32 v149, 1.0, v148
	v_add_f32_e32 v151, -1.0, v150
	v_sub_f32_e32 v149, v147, v149
	v_sub_f32_e32 v147, v147, v151
	v_add_f32_e32 v149, v146, v149
	v_add_f32_e32 v146, v146, v147
	v_add_f32_e32 v155, v150, v146
	v_rcp_f32_e32 v157, v155
	v_sub_f32_e32 v147, v150, v155
	v_add_f32_e32 v156, v146, v147
	v_add_f32_e32 v147, v148, v149
	v_mul_f32_e32 v159, v147, v157
	v_sub_f32_e32 v146, v148, v147
	v_mul_f32_e32 v148, v155, v159
	v_fma_f32 v150, v159, v155, -v148
	v_fmac_f32_e32 v150, v159, v156
	v_add_f32_e32 v158, v149, v146
	v_add_f32_e32 v146, v148, v150
	v_sub_f32_e32 v149, v147, v146
	v_pk_add_f32 v[152:153], v[146:147], v[148:149] neg_lo:[0,1] neg_hi:[0,1]
	v_mov_b32_e32 v151, v146
	v_pk_add_f32 v[146:147], v[152:153], v[150:151] neg_lo:[0,1] neg_hi:[0,1]
	v_cmp_neq_f32_e32 vcc, s37, v160
	v_add_f32_e32 v147, v158, v147
	v_add_f32_e32 v146, v146, v147
	v_add_f32_e32 v147, v149, v146
	v_mul_f32_e32 v158, v157, v147
	v_mul_f32_e32 v148, v155, v158
	v_fma_f32 v150, v158, v155, -v148
	v_fmac_f32_e32 v150, v158, v156
	v_sub_f32_e32 v149, v149, v147
	v_add_f32_e32 v155, v146, v149
	v_add_f32_e32 v146, v148, v150
	v_sub_f32_e32 v149, v147, v146
	v_pk_add_f32 v[152:153], v[146:147], v[148:149] neg_lo:[0,1] neg_hi:[0,1]
	v_mov_b32_e32 v151, v146
	v_pk_add_f32 v[146:147], v[152:153], v[150:151] neg_lo:[0,1] neg_hi:[0,1]
	s_nop 0
	v_add_f32_e32 v147, v155, v147
	v_add_f32_e32 v146, v146, v147
	v_add_f32_e32 v147, v159, v158
	v_add_f32_e32 v146, v149, v146
	v_sub_f32_e32 v148, v147, v159
	v_mul_f32_e32 v146, v157, v146
	v_sub_f32_e32 v148, v158, v148
	v_add_f32_e32 v148, v148, v146
	v_add_f32_e32 v150, v147, v148
	v_mul_f32_e32 v151, v150, v150
	v_fmamk_f32 v146, v151, 0x3e9b6dac, v183
	v_fmaak_f32 v177, v151, v146, 0x3f2aaada
	v_cvt_f32_i32_e32 v146, v154
	v_sub_f32_e32 v147, v150, v147
	v_sub_f32_e32 v147, v148, v147
	v_ldexp_f32 v152, v147, 1
	v_mul_f32_e32 v147, v150, v151
	v_ldexp_f32 v149, v150, 1
	v_pk_mul_f32 v[150:151], v[146:147], v[176:177]
	s_nop 0
	v_fma_f32 v148, v146, s43, -v150
	v_fmac_f32_e32 v148, 0xb102e308, v146
	v_pk_add_f32 v[146:147], v[150:151], v[148:149]
	s_nop 0
	v_sub_f32_e32 v149, v147, v149
	v_sub_f32_e32 v149, v151, v149
	v_add_f32_e32 v153, v152, v149
	v_mov_b32_e32 v152, v150
	v_pk_add_f32 v[150:151], v[146:147], v[150:151] neg_lo:[0,1] neg_hi:[0,1]
	v_pk_add_f32 v[154:155], v[146:147], v[152:153]
	v_mov_b32_e32 v149, v146
	v_mov_b32_e32 v151, v155
	v_pk_add_f32 v[156:157], v[148:149], v[150:151] neg_lo:[0,1] neg_hi:[0,1]
	v_pk_add_f32 v[148:149], v[148:149], v[150:151]
	v_mov_b32_e32 v152, v153
	v_pk_add_f32 v[150:151], v[148:149], v[146:147] op_sel:[1,0] op_sel_hi:[0,1] neg_lo:[0,1] neg_hi:[0,1]
	v_pk_add_f32 v[158:159], v[154:155], v[150:151] op_sel_hi:[1,0] neg_lo:[0,1] neg_hi:[0,1]
	v_mov_b32_e32 v154, v155
	v_mov_b32_e32 v155, v149
	v_pk_mov_b32 v[150:151], v[146:147], v[150:151] op_sel:[1,0]
	v_mov_b32_e32 v153, v146
	v_pk_add_f32 v[150:151], v[154:155], v[150:151] neg_lo:[0,1] neg_hi:[0,1]
	v_mov_b32_e32 v158, v156
	v_pk_add_f32 v[146:147], v[152:153], v[150:151] neg_lo:[0,1] neg_hi:[0,1]
	v_mov_b32_e32 v157, v149
	v_pk_add_f32 v[150:151], v[158:159], v[146:147]
	s_nop 0
	v_pk_add_f32 v[152:153], v[150:151], v[150:151] op_sel:[0,1] op_sel_hi:[1,0]
	s_nop 0
	v_pk_add_f32 v[148:149], v[148:149], v[152:153] op_sel:[1,0] op_sel_hi:[0,1]
	v_mov_b32_e32 v151, v148
	v_pk_add_f32 v[154:155], v[150:151], v[156:157] neg_lo:[0,1] neg_hi:[0,1]
	v_mov_b32_e32 v147, v152
	v_sub_f32_e32 v149, v150, v154
	v_pk_add_f32 v[146:147], v[146:147], v[154:155] neg_lo:[0,1] neg_hi:[0,1]
	v_sub_f32_e32 v149, v156, v149
	v_add_f32_e32 v146, v146, v149
	v_add_f32_e32 v146, v146, v147
	v_add_f32_e32 v146, v148, v146
	v_cndmask_b32_e32 v146, v184, v146, vcc
	v_cmp_lt_f32_e64 vcc, |v160|, s44
	s_nop 1
	v_cndmask_b32_e32 v146, v146, v160, vcc
	s_branch .LBB0_131
.LBB0_142:
	s_waitcnt vmcnt(0)
	s_or_b64 exec, exec, s[16:17]
	v_lshrrev_b32_e32 v1, 20, v0
	v_lshrrev_b32_e32 v0, 10, v0
	v_or_b32_e32 v0, v0, v1
	s_movk_i32 s0, 0x3ff
	v_and_or_b32 v0, v0, s0, v208
	v_cmp_eq_u32_e32 vcc, 0, v0
	s_waitcnt lgkmcnt(0)
	s_barrier
	s_and_saveexec_b64 s[0:1], vcc
	s_cbranch_execz .LBB0_152
	buffer_wbl2 sc1
	s_waitcnt vmcnt(0)
	s_load_dwordx2 s[2:3], s[14:15], 0x58
	v_mov_b32_e32 v2, 0
	s_mov_b64 s[4:5], exec
	v_mbcnt_lo_u32_b32 v1, s4, 0
	v_mbcnt_hi_u32_b32 v1, s5, v1
	s_waitcnt lgkmcnt(0)
	global_load_dword v0, v2, s[2:3] offset:40
	v_cmp_eq_u32_e32 vcc, 0, v1
	s_and_saveexec_b64 s[6:7], vcc
	s_cbranch_execz .LBB0_145
	s_bcnt1_i32_b64 s4, s[4:5]
	v_mov_b32_e32 v3, s4
	global_atomic_add v3, v2, v3, s[2:3] offset:32 sc0
